# attention PV stage rescheduled: V fragments read eight steps ahead, four accumulator chains
# speedup vs baseline: 1.0505x; 1.0007x over previous
.LBB0_500:
	s_lshl_b32 s4, s60, 6
	s_waitcnt lgkmcnt(0)
	v_add_f32_e32 v96, v96, v97
	v_lshl_add_u32 v97, s36, 6, v165
	v_add_u32_e32 v97, 0xf000, v97
	v_add_u32_e32 v114, 0x4000, v97
	v_add_u32_e32 v115, 0x8000, v97
	v_add_u32_e32 v116, 0xc000, v97
	ds_read2_b64 v[196:199], v97 offset1:4
	ds_read2_b64 v[200:203], v114 offset0:32 offset1:36
	ds_read2_b64 v[204:207], v115 offset0:64 offset1:68
	ds_read2_b64 v[208:211], v116 offset0:96 offset1:100
	ds_read2_b64 v[212:215], v97 offset0:8 offset1:12
	ds_read2_b64 v[216:219], v114 offset0:40 offset1:44
	ds_read2_b64 v[220:223], v115 offset0:72 offset1:76
	ds_read2_b64 v[224:227], v116 offset0:104 offset1:108
	s_lshl_b32 s4, s4, 1
	s_mov_b32 s59, s6
	s_mov_b32 s7, s58
	v_readlane_b32 s60, v250, 28
	s_waitcnt lgkmcnt(7)
	v_mfma_f32_16x16x32_bf16 v[228:231], v[196:199], v[92:95], 0
	ds_read2_b64 v[196:199], v97 offset0:16 offset1:20
	s_waitcnt lgkmcnt(7)
	v_mfma_f32_16x16x32_bf16 v[232:235], v[200:203], v[92:95], 0
	ds_read2_b64 v[200:203], v114 offset0:48 offset1:52
	s_waitcnt lgkmcnt(7)
	v_mfma_f32_16x16x32_bf16 v[236:239], v[204:207], v[92:95], 0
	ds_read2_b64 v[204:207], v115 offset0:80 offset1:84
	s_waitcnt lgkmcnt(7)
	v_mfma_f32_16x16x32_bf16 v[240:243], v[208:211], v[92:95], 0
	ds_read2_b64 v[208:211], v116 offset0:112 offset1:116
	s_waitcnt lgkmcnt(7)
	v_mfma_f32_16x16x32_bf16 v[228:231], v[212:215], v[88:91], v[228:231]
	ds_read2_b64 v[212:215], v97 offset0:24 offset1:28
	s_waitcnt lgkmcnt(7)
	v_mfma_f32_16x16x32_bf16 v[232:235], v[216:219], v[88:91], v[232:235]
	ds_read2_b64 v[216:219], v114 offset0:56 offset1:60
	s_waitcnt lgkmcnt(7)
	v_mfma_f32_16x16x32_bf16 v[236:239], v[220:223], v[88:91], v[236:239]
	ds_read2_b64 v[220:223], v115 offset0:88 offset1:92
	s_waitcnt lgkmcnt(7)
	v_mfma_f32_16x16x32_bf16 v[240:243], v[224:227], v[88:91], v[240:243]
	ds_read2_b64 v[224:227], v116 offset0:120 offset1:124
	s_waitcnt lgkmcnt(7)
	v_mfma_f32_16x16x32_bf16 v[228:231], v[196:199], v[84:87], v[228:231]
	ds_read2_b64 v[196:199], v97 offset0:32 offset1:36
	s_waitcnt lgkmcnt(7)
	v_mfma_f32_16x16x32_bf16 v[232:235], v[200:203], v[84:87], v[232:235]
	ds_read2_b64 v[200:203], v114 offset0:64 offset1:68
	s_waitcnt lgkmcnt(7)
	v_mfma_f32_16x16x32_bf16 v[236:239], v[204:207], v[84:87], v[236:239]
	ds_read2_b64 v[204:207], v115 offset0:96 offset1:100
	s_waitcnt lgkmcnt(7)
	v_mfma_f32_16x16x32_bf16 v[240:243], v[208:211], v[84:87], v[240:243]
	ds_read2_b64 v[208:211], v116 offset0:128 offset1:132
	s_waitcnt lgkmcnt(7)
	v_mfma_f32_16x16x32_bf16 v[228:231], v[212:215], v[80:83], v[228:231]
	ds_read2_b64 v[212:215], v97 offset0:40 offset1:44
	s_waitcnt lgkmcnt(7)
	v_mfma_f32_16x16x32_bf16 v[232:235], v[216:219], v[80:83], v[232:235]
	ds_read2_b64 v[216:219], v114 offset0:72 offset1:76
	s_waitcnt lgkmcnt(7)
	v_mfma_f32_16x16x32_bf16 v[236:239], v[220:223], v[80:83], v[236:239]
	ds_read2_b64 v[220:223], v115 offset0:104 offset1:108
	s_waitcnt lgkmcnt(7)
	v_mfma_f32_16x16x32_bf16 v[240:243], v[224:227], v[80:83], v[240:243]
	ds_read2_b64 v[224:227], v116 offset0:136 offset1:140
	s_waitcnt lgkmcnt(7)
	v_mfma_f32_16x16x32_bf16 v[228:231], v[196:199], v[76:79], v[228:231]
	ds_read2_b64 v[196:199], v97 offset0:48 offset1:52
	s_waitcnt lgkmcnt(7)
	v_mfma_f32_16x16x32_bf16 v[232:235], v[200:203], v[76:79], v[232:235]
	ds_read2_b64 v[200:203], v114 offset0:80 offset1:84
	s_waitcnt lgkmcnt(7)
	v_mfma_f32_16x16x32_bf16 v[236:239], v[204:207], v[76:79], v[236:239]
	ds_read2_b64 v[204:207], v115 offset0:112 offset1:116
	s_waitcnt lgkmcnt(7)
	v_mfma_f32_16x16x32_bf16 v[240:243], v[208:211], v[76:79], v[240:243]
	ds_read2_b64 v[208:211], v116 offset0:144 offset1:148
	s_waitcnt lgkmcnt(7)
	v_mfma_f32_16x16x32_bf16 v[228:231], v[212:215], v[72:75], v[228:231]
	ds_read2_b64 v[212:215], v97 offset0:56 offset1:60
	s_waitcnt lgkmcnt(7)
	v_mfma_f32_16x16x32_bf16 v[232:235], v[216:219], v[72:75], v[232:235]
	ds_read2_b64 v[216:219], v114 offset0:88 offset1:92
	s_waitcnt lgkmcnt(7)
	v_mfma_f32_16x16x32_bf16 v[236:239], v[220:223], v[72:75], v[236:239]
	ds_read2_b64 v[220:223], v115 offset0:120 offset1:124
	s_waitcnt lgkmcnt(7)
	v_mfma_f32_16x16x32_bf16 v[240:243], v[224:227], v[72:75], v[240:243]
	ds_read2_b64 v[224:227], v116 offset0:152 offset1:156
	s_waitcnt lgkmcnt(7)
	v_mfma_f32_16x16x32_bf16 v[228:231], v[196:199], v[68:71], v[228:231]
	s_waitcnt lgkmcnt(6)
	v_mfma_f32_16x16x32_bf16 v[232:235], v[200:203], v[68:71], v[232:235]
	s_waitcnt lgkmcnt(5)
	v_mfma_f32_16x16x32_bf16 v[236:239], v[204:207], v[68:71], v[236:239]
	s_waitcnt lgkmcnt(4)
	v_mfma_f32_16x16x32_bf16 v[240:243], v[208:211], v[68:71], v[240:243]
	s_waitcnt lgkmcnt(3)
	v_mfma_f32_16x16x32_bf16 v[72:75], v[212:215], v[64:67], v[228:231]
	s_waitcnt lgkmcnt(2)
	v_mfma_f32_16x16x32_bf16 v[76:79], v[216:219], v[64:67], v[232:235]
	s_waitcnt lgkmcnt(1)
	v_mfma_f32_16x16x32_bf16 v[80:83], v[220:223], v[64:67], v[236:239]
	s_waitcnt lgkmcnt(0)
	v_mfma_f32_16x16x32_bf16 v[64:67], v[224:227], v[64:67], v[240:243]
	s_nop 2
	v_div_scale_f32 v68, s[8:9], v96, v96, 1.0
	v_rcp_f32_e32 v69, v68
	v_readlane_b32 s8, v251, 37
	v_readlane_b32 s9, v251, 38
	s_add_u32 s4, s8, s4
	v_fma_f32 v70, -v68, v69, 1.0
	v_fmac_f32_e32 v69, v70, v69
	v_div_scale_f32 v70, vcc, 1.0, v96, 1.0
	v_mul_f32_e32 v71, v70, v69
	v_fma_f32 v84, -v68, v71, v70
	v_fmac_f32_e32 v71, v84, v69
	v_fma_f32 v68, -v68, v71, v70
	v_div_fmas_f32 v68, v68, v69, v71
	v_div_fixup_f32 v84, v68, v96, 1.0
	s_addc_u32 s5, s9, 0
	v_lshlrev_b64 v[68:69], 10, v[142:143]
	v_lshl_add_u64 v[68:69], s[4:5], 0, v[68:69]
	v_lshlrev_b32_e32 v70, 1, v138
	v_mov_b32_e32 v71, v145
	v_lshl_add_u64 v[68:69], v[68:69], 0, v[70:71]
	v_mul_f32_e32 v70, v84, v72
	v_mul_f32_e32 v71, v84, v73
	v_cvt_pk_bf16_f32 v70, v70, v71
	v_mul_f32_e32 v71, v84, v74
	v_mul_f32_e32 v72, v84, v75
	v_cvt_pk_bf16_f32 v71, v71, v72
	global_store_dwordx2 v[68:69], v[70:71], off
	v_mul_f32_e32 v70, v84, v76
	v_mul_f32_e32 v71, v84, v77
	v_cvt_pk_bf16_f32 v70, v70, v71
	v_mul_f32_e32 v71, v84, v78
	v_mul_f32_e32 v72, v84, v79
	v_cvt_pk_bf16_f32 v71, v71, v72
	global_store_dwordx2 v[68:69], v[70:71], off offset:32
	v_mul_f32_e32 v70, v84, v80
	v_mul_f32_e32 v71, v84, v81
	v_readlane_b32 s4, v250, 14
	v_cvt_pk_bf16_f32 v70, v70, v71
	v_mul_f32_e32 v71, v84, v82
	v_mul_f32_e32 v64, v84, v64
	v_mul_f32_e32 v65, v84, v65
	s_add_i32 s57, s57, s4
	v_readlane_b32 s4, v250, 15
	v_mul_f32_e32 v72, v84, v83
	v_cvt_pk_bf16_f32 v71, v71, v72
	global_store_dwordx2 v[68:69], v[70:71], off offset:64
	v_cvt_pk_bf16_f32 v64, v64, v65
	v_mul_f32_e32 v65, v84, v66
	s_add_i32 s56, s56, s4
	s_and_b64 vcc, exec, s[44:45]
	v_mul_f32_e32 v66, v84, v67
	v_cvt_pk_bf16_f32 v65, v65, v66
	global_store_dwordx2 v[68:69], v[64:65], off offset:96
	s_cbranch_vccz .LBB0_806
